# attention S2 schedule variant h (h: exps/cvts first in head; b: rebalanced row-sum adds)
# baseline (speedup 1.0000x reference)
; #define LOADV(dst, ks_) do { _Pragma("unroll") for (int dvb = 0; dvb < 4; ++dvb) { dst[2 * dvb] = vtr(vp + dvb * 4096 + (ks_) * 1024); dst[2 * dvb + 1] = vtr(vp + dvb * 4096 + (ks_) * 1024 + 512); } } while (0)
; #define MF4(src, pfrag) do { _Pragma("unroll") for (int dvb = 0; dvb < 4; ++dvb) { \
;         const bf16x8 vf_ = __builtin_shufflevector(src[2 * dvb], src[2 * dvb + 1], 0, 1, 2, 3, 4, 5, 6, 7); o[dvb] = MFMA32(vf_, pfrag, o[dvb]); } } while (0)
; #define EXPQ(S, lo_, RS, PF) do { _Pragma("unroll") for (int i = lo_; i < lo_ + 8; ++i) { S[i] = ex2(S[i]); RS += S[i]; } \
;               u32x4 w_; w_.x = pk2(S[lo_], S[lo_ + 1]); w_.y = pk2(S[lo_ + 2], S[lo_ + 3]); w_.z = pk2(S[lo_ + 4], S[lo_ + 5]); w_.w = pk2(S[lo_ + 6], S[lo_ + 7]); PF = __builtin_bit_cast(bf16x8, w_); } while (0)
; DI void attn_unit(const Params& p, int bh, int qb, char* lds, float lam, int tid, int lane, int wid, const bool build_tab) {
;     ...
;             float rs0 = 0.f, rs1 = 0.f;
;     ...
;             EXPQ(s0, 0, rs0, pf[0]);
;             LOADV(vb, 1);
;             MF4(va, pf[0]);
;             EXPQ(s0, 8, rs1, pf[1]);
;             LOADV(va, 2);
;             MF4(vb, pf[1]);
;             EXPQ(s1, 0, rs0, pf[2]);
;             LOADV(vb, 3);
;             MF4(va, pf[2]);
;             EXPQ(s1, 8, rs1, pf[3]);
;             MF4(vb, pf[3]);
;             l += rs0 + rs1;
.LBB0_359:
	v_exp_f32_e32 v222, v96
	v_exp_f32_e32 v224, v97
	v_exp_f32_e32 v226, v98
	v_exp_f32_e32 v228, v99
	v_exp_f32_e32 v230, v100
	v_exp_f32_e32 v232, v101
	v_exp_f32_e32 v234, v102
	v_exp_f32_e32 v236, v103
	v_cvt_pk_bf16_f32 v96, v222, v224
	v_cvt_pk_bf16_f32 v97, v226, v228
	v_cvt_pk_bf16_f32 v98, v230, v232
	v_cvt_pk_bf16_f32 v99, v234, v236
	ds_read_b64_tr_b16 v[100:101], v220 offset:17408
	ds_read_b64_tr_b16 v[102:103], v220 offset:17920
	ds_read_b64_tr_b16 v[242:243], v220 offset:21504
	ds_read_b64_tr_b16 v[244:245], v220 offset:22016
	s_waitcnt lgkmcnt(10)
	v_mfma_f32_32x32x16_bf16 v[48:63], v[140:143], v[96:99], v[48:63]
	ds_read_b64_tr_b16 v[246:247], v220 offset:25600
	ds_read_b64_tr_b16 v[248:249], v220 offset:26112
	ds_read_b64_tr_b16 v[250:251], v220 offset:29696
	ds_read_b64_tr_b16 v[252:253], v220 offset:30208
	v_exp_f32_e32 v223, v104
	v_exp_f32_e32 v225, v105
	v_exp_f32_e32 v227, v106
	v_add_f32_e32 v221, v224, v222
	s_waitcnt lgkmcnt(12)
	v_mfma_f32_32x32x16_bf16 v[32:47], v[136:139], v[96:99], v[32:47]
	v_exp_f32_e32 v229, v107
	v_exp_f32_e32 v231, v108
	v_exp_f32_e32 v233, v109
	v_add_f32_e32 v221, v226, v221
	s_waitcnt lgkmcnt(10)
	v_mfma_f32_32x32x16_bf16 v[16:31], v[132:135], v[96:99], v[16:31]
	v_exp_f32_e32 v235, v110
	v_exp_f32_e32 v237, v111
	v_add_f32_e32 v221, v228, v221
	v_add_f32_e32 v221, v230, v221
	ds_read_b64_tr_b16 v[104:105], v220 offset:18432
	ds_read_b64_tr_b16 v[106:107], v220 offset:18944
	ds_read_b64_tr_b16 v[108:109], v220 offset:19456
	ds_read_b64_tr_b16 v[110:111], v220 offset:19968
	s_waitcnt lgkmcnt(12)
	v_mfma_f32_32x32x16_bf16 v[0:15], v[128:131], v[96:99], v[0:15]
	ds_read_b64_tr_b16 v[128:129], v220 offset:26624
	ds_read_b64_tr_b16 v[130:131], v220 offset:27136
	v_cvt_pk_bf16_f32 v96, v223, v225
	v_cvt_pk_bf16_f32 v97, v227, v229
	v_cvt_pk_bf16_f32 v98, v231, v233
	v_cvt_pk_bf16_f32 v99, v235, v237
	v_exp_f32_e32 v140, v84
	v_exp_f32_e32 v142, v85
	s_waitcnt lgkmcnt(12)
	v_mfma_f32_32x32x16_bf16 v[48:63], v[100:103], v[96:99], v[48:63]
	v_exp_f32_e32 v238, v86
	v_exp_f32_e32 v240, v87
	v_add_f32_e32 v221, v232, v221
	ds_read_b64_tr_b16 v[84:85], v220 offset:22528
	ds_read_b64_tr_b16 v[86:87], v220 offset:23040
	v_exp_f32_e32 v136, v82
	s_waitcnt lgkmcnt(12)
	v_mfma_f32_32x32x16_bf16 v[32:47], v[242:245], v[96:99], v[32:47]
	ds_read_b64_tr_b16 v[242:243], v220 offset:23552
	ds_read_b64_tr_b16 v[244:245], v220 offset:24064
	v_exp_f32_e32 v138, v83
	v_exp_f32_e32 v132, v80
	v_exp_f32_e32 v134, v81
	v_add_f32_e32 v221, v234, v221
	s_waitcnt lgkmcnt(12)
	v_mfma_f32_32x32x16_bf16 v[16:31], v[246:249], v[96:99], v[16:31]
	ds_read_b64_tr_b16 v[246:247], v220 offset:27648
	ds_read_b64_tr_b16 v[248:249], v220 offset:28160
	v_cvt_pk_bf16_f32 v80, v132, v134
	v_cvt_pk_bf16_f32 v81, v136, v138
	v_cvt_pk_bf16_f32 v82, v140, v142
	v_cvt_pk_bf16_f32 v83, v238, v240
	v_exp_f32_e32 v133, v88
	v_exp_f32_e32 v135, v89
	s_waitcnt lgkmcnt(12)
	v_mfma_f32_32x32x16_bf16 v[0:15], v[250:253], v[96:99], v[0:15]
	ds_read_b64_tr_b16 v[250:251], v220 offset:31744
	ds_read_b64_tr_b16 v[252:253], v220 offset:32256
	v_exp_f32_e32 v137, v90
	v_exp_f32_e32 v139, v91
	v_add_f32_e32 v221, v236, v221
	ds_read_b64_tr_b16 v[88:89], v220 offset:30720
	ds_read_b64_tr_b16 v[90:91], v220 offset:31232
	v_exp_f32_e32 v141, v92
	s_waitcnt lgkmcnt(14)
	v_mfma_f32_32x32x16_bf16 v[48:63], v[104:107], v[80:83], v[48:63]
	v_exp_f32_e32 v143, v93
	v_exp_f32_e32 v239, v94
	v_exp_f32_e32 v241, v95
	v_add_f32_e32 v221, v132, v221
	s_waitcnt lgkmcnt(8)
	v_mfma_f32_32x32x16_bf16 v[32:47], v[84:87], v[80:83], v[32:47]
	v_add_f32_e32 v93, v225, v223
	v_add_f32_e32 v221, v134, v221
	v_add_f32_e32 v93, v227, v93
	v_add_f32_e32 v221, v136, v221
	v_add_f32_e32 v93, v229, v93
	v_add_f32_e32 v221, v138, v221
	s_waitcnt lgkmcnt(10)
	v_mfma_f32_32x32x16_bf16 v[16:31], v[128:131], v[80:83], v[16:31]
	v_add_f32_e32 v93, v231, v93
	v_add_f32_e32 v221, v140, v221
	v_add_f32_e32 v93, v233, v93
	v_add_f32_e32 v221, v142, v221
	v_add_f32_e32 v93, v235, v93
	v_add_f32_e32 v221, v238, v221
	v_add_f32_e32 v93, v237, v93
	s_waitcnt lgkmcnt(0)
	v_mfma_f32_32x32x16_bf16 v[0:15], v[88:91], v[80:83], v[0:15]
	v_cvt_pk_bf16_f32 v80, v133, v135
	v_cvt_pk_bf16_f32 v81, v137, v139
	v_cvt_pk_bf16_f32 v82, v141, v143
	v_cvt_pk_bf16_f32 v83, v239, v241
	v_add_f32_e32 v221, v240, v221
	v_add_f32_e32 v93, v133, v93
	s_waitcnt lgkmcnt(12)
	v_mfma_f32_32x32x16_bf16 v[48:63], v[108:111], v[80:83], v[48:63]
	v_add_f32_e32 v93, v135, v93
	v_add_f32_e32 v93, v137, v93
	s_waitcnt lgkmcnt(6)
	v_mfma_f32_32x32x16_bf16 v[32:47], v[242:245], v[80:83], v[32:47]
	v_add_f32_e32 v93, v139, v93
	v_add_f32_e32 v93, v141, v93
	s_waitcnt lgkmcnt(4)
	v_mfma_f32_32x32x16_bf16 v[16:31], v[246:249], v[80:83], v[16:31]
	v_add_f32_e32 v93, v143, v93
	v_add_f32_e32 v93, v239, v93
	s_waitcnt lgkmcnt(2)
	v_mfma_f32_32x32x16_bf16 v[0:15], v[250:253], v[80:83], v[0:15]
	v_add_f32_e32 v93, v241, v93
	v_add_f32_e32 v221, v221, v93
	v_add_f32_e32 v146, v146, v221

; #define LOADV(dst, ks_) do { _Pragma("unroll") for (int dvb = 0; dvb < 4; ++dvb) { dst[2 * dvb] = vtr(vp + dvb * 4096 + (ks_) * 1024); dst[2 * dvb + 1] = vtr(vp + dvb * 4096 + (ks_) * 1024 + 512); } } while (0)
; #define MF4(src, pfrag) do { _Pragma("unroll") for (int dvb = 0; dvb < 4; ++dvb) { \
;         const bf16x8 vf_ = __builtin_shufflevector(src[2 * dvb], src[2 * dvb + 1], 0, 1, 2, 3, 4, 5, 6, 7); o[dvb] = MFMA32(vf_, pfrag, o[dvb]); } } while (0)
; #define EXPQ(S, lo_, RS, PF) do { _Pragma("unroll") for (int i = lo_; i < lo_ + 8; ++i) { S[i] = ex2(S[i]); RS += S[i]; } \
;               u32x4 w_; w_.x = pk2(S[lo_], S[lo_ + 1]); w_.y = pk2(S[lo_ + 2], S[lo_ + 3]); w_.z = pk2(S[lo_ + 4], S[lo_ + 5]); w_.w = pk2(S[lo_ + 6], S[lo_ + 7]); PF = __builtin_bit_cast(bf16x8, w_); } while (0)
; DI void attn_unit(const Params& p, int bh, int qb, char* lds, float lam, int tid, int lane, int wid, const bool build_tab) {
;     ...
;             float rs0 = 0.f, rs1 = 0.f;
;     ...
;             EXPQ(s0, 0, rs0, pf[0]);
;             LOADV(vb, 1);
;             MF4(va, pf[0]);
;             EXPQ(s0, 8, rs1, pf[1]);
;             LOADV(va, 2);
;             MF4(vb, pf[1]);
;             EXPQ(s1, 0, rs0, pf[2]);
;             LOADV(vb, 3);
;             MF4(va, pf[2]);
;             EXPQ(s1, 8, rs1, pf[3]);
;             MF4(vb, pf[3]);
;             l += rs0 + rs1;
.LBB0_379:
	v_exp_f32_e32 v178, v96
	v_exp_f32_e32 v180, v97
	v_exp_f32_e32 v182, v98
	v_exp_f32_e32 v184, v99
	v_exp_f32_e32 v186, v100
	v_exp_f32_e32 v188, v101
	v_exp_f32_e32 v190, v102
	v_exp_f32_e32 v192, v103
	v_cvt_pk_bf16_f32 v96, v178, v180
	v_cvt_pk_bf16_f32 v97, v182, v184
	v_cvt_pk_bf16_f32 v98, v186, v188
	v_cvt_pk_bf16_f32 v99, v190, v192
	ds_read_b64_tr_b16 v[100:101], v177 offset:17408
	ds_read_b64_tr_b16 v[102:103], v177 offset:17920
	ds_read_b64_tr_b16 v[230:231], v177 offset:21504
	ds_read_b64_tr_b16 v[232:233], v177 offset:22016
	s_waitcnt lgkmcnt(10)
	v_mfma_f32_32x32x16_bf16 v[48:63], v[140:143], v[96:99], v[48:63]
	ds_read_b64_tr_b16 v[234:235], v177 offset:25600
	ds_read_b64_tr_b16 v[236:237], v177 offset:26112
	ds_read_b64_tr_b16 v[238:239], v177 offset:29696
	ds_read_b64_tr_b16 v[240:241], v177 offset:30208
	v_exp_f32_e32 v179, v104
	v_exp_f32_e32 v181, v105
	v_exp_f32_e32 v183, v106
	v_add_f32_e32 v242, v180, v178
	s_waitcnt lgkmcnt(12)
	v_mfma_f32_32x32x16_bf16 v[32:47], v[136:139], v[96:99], v[32:47]
	v_exp_f32_e32 v185, v107
	v_exp_f32_e32 v187, v108
	v_exp_f32_e32 v189, v109
	v_add_f32_e32 v242, v182, v242
	s_waitcnt lgkmcnt(10)
	v_mfma_f32_32x32x16_bf16 v[16:31], v[132:135], v[96:99], v[16:31]
	v_exp_f32_e32 v191, v110
	v_exp_f32_e32 v193, v111
	v_add_f32_e32 v242, v184, v242
	v_add_f32_e32 v242, v186, v242
	ds_read_b64_tr_b16 v[104:105], v177 offset:18432
	ds_read_b64_tr_b16 v[106:107], v177 offset:18944
	ds_read_b64_tr_b16 v[108:109], v177 offset:19456
	ds_read_b64_tr_b16 v[110:111], v177 offset:19968
	s_waitcnt lgkmcnt(12)
	v_mfma_f32_32x32x16_bf16 v[0:15], v[128:131], v[96:99], v[0:15]
	ds_read_b64_tr_b16 v[128:129], v177 offset:26624
	ds_read_b64_tr_b16 v[130:131], v177 offset:27136
	v_cvt_pk_bf16_f32 v96, v179, v181
	v_cvt_pk_bf16_f32 v97, v183, v185
	v_cvt_pk_bf16_f32 v98, v187, v189
	v_cvt_pk_bf16_f32 v99, v191, v193
	v_exp_f32_e32 v140, v84
	v_exp_f32_e32 v142, v85
	s_waitcnt lgkmcnt(12)
	v_mfma_f32_32x32x16_bf16 v[48:63], v[100:103], v[96:99], v[48:63]
	v_exp_f32_e32 v194, v86
	v_exp_f32_e32 v196, v87
	v_add_f32_e32 v242, v188, v242
	ds_read_b64_tr_b16 v[84:85], v177 offset:22528
	ds_read_b64_tr_b16 v[86:87], v177 offset:23040
	v_exp_f32_e32 v136, v82
	s_waitcnt lgkmcnt(12)
	v_mfma_f32_32x32x16_bf16 v[32:47], v[230:233], v[96:99], v[32:47]
	ds_read_b64_tr_b16 v[230:231], v177 offset:23552
	ds_read_b64_tr_b16 v[232:233], v177 offset:24064
	v_exp_f32_e32 v138, v83
	v_exp_f32_e32 v132, v80
	v_exp_f32_e32 v134, v81
	v_add_f32_e32 v242, v190, v242
	s_waitcnt lgkmcnt(12)
	v_mfma_f32_32x32x16_bf16 v[16:31], v[234:237], v[96:99], v[16:31]
	ds_read_b64_tr_b16 v[234:235], v177 offset:27648
	ds_read_b64_tr_b16 v[236:237], v177 offset:28160
	v_cvt_pk_bf16_f32 v80, v132, v134
	v_cvt_pk_bf16_f32 v81, v136, v138
	v_cvt_pk_bf16_f32 v82, v140, v142
	v_cvt_pk_bf16_f32 v83, v194, v196
	v_exp_f32_e32 v133, v88
	v_exp_f32_e32 v135, v89
	s_waitcnt lgkmcnt(12)
	v_mfma_f32_32x32x16_bf16 v[0:15], v[238:241], v[96:99], v[0:15]
	ds_read_b64_tr_b16 v[238:239], v177 offset:31744
	ds_read_b64_tr_b16 v[240:241], v177 offset:32256
	v_exp_f32_e32 v137, v90
	v_exp_f32_e32 v139, v91
	v_add_f32_e32 v242, v192, v242
	ds_read_b64_tr_b16 v[88:89], v177 offset:30720
	ds_read_b64_tr_b16 v[90:91], v177 offset:31232
	v_exp_f32_e32 v141, v92
	s_waitcnt lgkmcnt(14)
	v_mfma_f32_32x32x16_bf16 v[48:63], v[104:107], v[80:83], v[48:63]
	v_exp_f32_e32 v143, v93
	v_exp_f32_e32 v195, v94
	v_exp_f32_e32 v197, v95
	v_add_f32_e32 v242, v132, v242
	s_waitcnt lgkmcnt(8)
	v_mfma_f32_32x32x16_bf16 v[32:47], v[84:87], v[80:83], v[32:47]
	v_add_f32_e32 v243, v181, v179
	v_add_f32_e32 v242, v134, v242
	v_add_f32_e32 v243, v183, v243
	v_add_f32_e32 v242, v136, v242
	v_add_f32_e32 v243, v185, v243
	v_add_f32_e32 v242, v138, v242
	s_waitcnt lgkmcnt(10)
	v_mfma_f32_32x32x16_bf16 v[16:31], v[128:131], v[80:83], v[16:31]
	v_add_f32_e32 v243, v187, v243
	v_add_f32_e32 v242, v140, v242
	v_add_f32_e32 v243, v189, v243
	v_add_f32_e32 v242, v142, v242
	v_add_f32_e32 v243, v191, v243
	v_add_f32_e32 v242, v194, v242
	v_add_f32_e32 v243, v193, v243
	s_waitcnt lgkmcnt(0)
	v_mfma_f32_32x32x16_bf16 v[0:15], v[88:91], v[80:83], v[0:15]
	v_cvt_pk_bf16_f32 v80, v133, v135
	v_cvt_pk_bf16_f32 v81, v137, v139
	v_cvt_pk_bf16_f32 v82, v141, v143
	v_cvt_pk_bf16_f32 v83, v195, v197
	v_add_f32_e32 v242, v196, v242
	v_add_f32_e32 v243, v133, v243
	s_waitcnt lgkmcnt(12)
	v_mfma_f32_32x32x16_bf16 v[48:63], v[108:111], v[80:83], v[48:63]
	v_add_f32_e32 v243, v135, v243
	v_add_f32_e32 v243, v137, v243
	s_waitcnt lgkmcnt(6)
	v_mfma_f32_32x32x16_bf16 v[32:47], v[230:233], v[80:83], v[32:47]
	v_add_f32_e32 v243, v139, v243
	v_add_f32_e32 v243, v141, v243
	s_waitcnt lgkmcnt(4)
	v_mfma_f32_32x32x16_bf16 v[16:31], v[234:237], v[80:83], v[16:31]
	v_add_f32_e32 v243, v143, v243
	v_add_f32_e32 v243, v195, v243
	s_waitcnt lgkmcnt(2)
	v_mfma_f32_32x32x16_bf16 v[0:15], v[238:241], v[80:83], v[0:15]
	v_add_f32_e32 v243, v197, v243
	v_add_f32_e32 v242, v242, v243
	v_add_f32_e32 v176, v176, v242
